# inter-chunk state scan as loader/consumer pipeline: waves 4-7 LDS-DMA round r+2 into a double-buffered LDS slot, waves 0-3 consume round r
# speedup vs baseline: 1.0433x; 1.0051x over previous
.LBB0_32:
	s_add_u32 s24, s20, 0x7600000
	s_addc_u32 s25, s21, 0
	s_add_u32 s46, s20, 0x280000
	s_addc_u32 s47, s21, 0
	s_bfe_u32 s15, s12, 0x10007
	v_mov_b32_e32 v0, 0x6050400
	s_lshl_b32 s16, s15, 24
	v_perm_b32 v165, s12, v164, v0
	s_add_u32 s16, s24, s16
	v_and_b32_e32 v0, 0x7fff, v165
	s_addc_u32 s17, s25, 0
	s_lshl_b32 s15, s15, 12
	v_lshlrev_b32_e32 v162, 2, v0
	s_add_u32 s15, s46, s15
	v_lshl_add_u64 v[166:167], s[16:17], 0, v[162:163]
	s_addc_u32 s16, s47, 0
	s_lshr_b32 s17, s12, 2
	s_and_b32 s17, s17, 28
	s_mov_b32 s0, 0x10000
	v_cmp_gt_i32_e64 s[22:23], s2, v164
	s_add_u32 s58, s15, s17
	v_cmp_gt_i32_e32 vcc, s0, v165
	s_addc_u32 s59, s16, 0
	s_and_b64 s[16:17], s[22:23], vcc
	v_cndmask_b32_e64 v168, v219, 0, s[16:17]
	v_readfirstlane_b32 s88, v164
	v_lshrrev_b32_e32 v246, 6, v164
	v_and_b32_e32 v246, 3, v246
	v_lshlrev_b32_e32 v246, 13, v246
	v_add_u32_e32 v246, 0x1b000, v246
	s_lshr_b32 s73, s88, 6
	s_and_b32 s73, s73, 3
	s_lshl_b32 s73, s73, 13
	s_add_i32 s73, s73, 0x1b000
	s_lshr_b32 s88, s88, 8
	v_lshl_add_u32 v246, v229, 2, v246
	s_mov_b32 s89, 0
	s_mov_b32 s94, 0
	s_mov_b32 s95, 0
	s_add_i32 s15, s68, 5
	s_lshl_b32 s81, s80, 2
	s_lshl_b32 s16, s12, 2
	s_cmp_lt_u32 s15, 13
	s_movk_i32 s15, 0x3d00
	s_cselect_b32 s15, s15, 0x6200
	s_movk_i32 s17, 0x3500
	s_cselect_b32 s17, s17, 0x5e00
	v_mov_b32_e32 v1, s15
	s_movk_i32 s15, 0xbfc
	v_mov_b32_e32 v0, s17
	s_cselect_b32 s15, s15, 0x3cfc
	v_cndmask_b32_e64 v230, v0, v1, s[22:23]
	v_mov_b32_e32 v1, s15
	v_writelane_b32 v255, s22, 8
	s_add_i32 s15, s37, s16
	v_lshrrev_b32_e32 v232, 2, v229
	v_cndmask_b32_e64 v0, v1, v0, s[22:23]
	v_add_u32_e32 v231, s15, v0
	v_mov_b32_e32 v231, v230
	s_mul_i32 s15, s37, 0x1100
	s_add_i32 s15, s15, 0
	v_writelane_b32 v255, s23, 9
	s_add_i32 s22, s15, 0x12800
	s_add_u32 s26, s20, 0x1000000
	s_addc_u32 s27, s21, 0
	s_add_u32 s28, s20, 0x1400000
	s_addc_u32 s29, s21, 0
	s_add_u32 s30, s20, 0x2a00000
	s_addc_u32 s31, s21, 0
	s_cmpk_gt_i32 s96, 0xff
	v_and_b32_e32 v235, 60, v229
	v_or_b32_e32 v233, 16, v232
	v_writelane_b32 v255, s37, 10
	s_cbranch_scc1 .LBB0_144
	s_add_u32 s98, s20, 0x5600000
	s_addc_u32 s99, s21, 0
	v_lshlrev_b32_e32 v1, 3, v229
	s_add_u32 s15, s20, 0x9600000
	v_and_b32_e32 v0, 31, v164
	v_lshrrev_b32_e32 v178, 5, v229
	v_and_b32_e32 v18, 24, v1
	s_addc_u32 s40, s21, 0
	v_lshl_add_u32 v19, v0, 2, s22
	v_mul_u32_u24_e32 v20, 0x84, v178
	v_mul_u32_u24_e32 v1, 0x84, v18
	s_lshl_b32 s16, s96, 6
	v_writelane_b32 v255, s22, 11
	v_add3_u32 v1, s22, v1, v235
	v_cmp_gt_u32_e64 s[42:43], 8, v0
	v_mov_b32_e32 v179, v163
	s_add_i32 s41, s16, 0xfffffe40
	s_lshl_b32 s22, s80, 6
	v_mov_b32_e32 v176, v163
	v_mov_b32_e32 v177, v163
	s_waitcnt vmcnt(0)
	v_mov_b32_e32 v2, v163
	v_mov_b32_e32 v3, v163
	v_mov_b32_e32 v4, v163
	v_mov_b32_e32 v5, v163
	v_mov_b32_e32 v6, v163
	v_mov_b32_e32 v7, v163
	v_mov_b32_e32 v8, v163
	v_mov_b32_e32 v9, v163
	v_mov_b32_e32 v10, v163
	v_mov_b32_e32 v11, v163
	v_mov_b32_e32 v12, v163
	v_mov_b32_e32 v13, v163
	v_mov_b32_e32 v14, v163
	v_mov_b32_e32 v15, v163
	v_mov_b32_e32 v16, v163
	v_mov_b32_e32 v17, v163
	v_mov_b32_e32 v234, 0x400
	v_mov_b32_e32 v236, 0
	s_mov_b64 s[36:37], 0
	v_mov_b64_e32 v[170:171], s[18:19]
	v_mov_b64_e32 v[172:173], s[54:55]
	v_lshlrev_b32_e32 v162, 2, v0
	v_lshlrev_b32_e32 v180, 1, v18
	v_add_u32_e32 v237, v19, v20
	v_mov_b32_e32 v0, 0
	v_mov_b32_e32 v174, 0
	s_branch .LBB0_35

.LBB0_35:
	v_mov_b32_e32 v44, v164
	s_lshl_b32 s35, s96, 6
	v_readfirstlane_b32 s34, v44
	v_and_b32_e32 v45, 15, v44
	s_ashr_i32 s38, s34, 7
	s_lshr_b32 s16, s34, 1
	v_and_or_b32 v78, s16, 32, v45
	s_lshl_b32 s16, s38, 6
	s_ashr_i32 s17, s16, 31
	s_lshl_b64 s[92:93], s[16:17], 1
	s_add_u32 s16, s15, s92
	v_or_b32_e32 v186, s35, v78
	s_addc_u32 s17, s40, s93
	v_and_b32_e32 v18, 48, v44
	v_mov_b32_e32 v19, v163
	v_lshl_add_u64 v[20:21], s[16:17], 0, v[18:19]
	v_or_b32_e32 v182, 16, v186
	v_mad_i64_i32 v[22:23], s[16:17], v186, s76, v[20:21]
	v_mad_i64_i32 v[20:21], s[16:17], v182, s76, v[20:21]
	s_and_b32 s16, s96, 0x7f
	s_sub_i32 s17, 8, s16
	s_cmp_lt_u32 s16, 8
	s_cselect_b32 s23, s17, 0
	s_lshl_b32 s39, s23, 6
	s_add_i32 s16, s35, s39
	s_addk_i32 s16, 0xfe00
	global_load_dwordx4 v[26:29], v[22:23], off
	global_load_dwordx4 v[30:33], v[22:23], off offset:64
	v_add_u32_e32 v22, 0x200, v44
	s_mul_hi_i32 s17, s16, 0x1600
	s_mulk_i32 s16, 0x1600
	v_ashrrev_i32_e32 v79, 5, v22
	v_add_u32_e32 v22, 0x400, v44
	s_add_u32 s16, s15, s16
	v_lshlrev_b32_e32 v19, 3, v44
	v_ashrrev_i32_e32 v80, 5, v22
	v_add_u32_e32 v22, 0x600, v44
	s_addc_u32 s17, s40, s17
	global_load_dwordx4 v[34:37], v[20:21], off
	global_load_dwordx4 v[38:41], v[20:21], off offset:64
	v_and_b32_e32 v20, 0xf8, v19
	v_ashrrev_i32_e32 v81, 5, v22
	v_mov_b64_e32 v[22:23], s[16:17]
	v_mad_i64_i32 v[24:25], s[16:17], v81, s76, v[22:23]
	v_lshlrev_b32_e32 v42, 1, v20
	v_mov_b32_e32 v43, v163
	v_lshl_add_u64 v[24:25], v[24:25], 0, v[42:43]
	global_load_dwordx4 v[62:65], v[24:25], off offset:1024
	global_load_dwordx4 v[46:49], v[24:25], off offset:512
	v_mad_i64_i32 v[24:25], s[16:17], v80, s76, v[22:23]
	v_ashrrev_i32_e32 v21, 5, v44
	v_lshl_add_u64 v[24:25], v[24:25], 0, v[42:43]
	global_load_dwordx4 v[66:69], v[24:25], off offset:1024
	global_load_dwordx4 v[50:53], v[24:25], off offset:512
	v_mad_i64_i32 v[24:25], s[16:17], v79, s76, v[22:23]
	v_mad_i64_i32 v[22:23], s[16:17], v21, s76, v[22:23]
	v_lshl_add_u64 v[24:25], v[24:25], 0, v[42:43]
	v_lshl_add_u64 v[22:23], v[22:23], 0, v[42:43]
	global_load_dwordx4 v[70:73], v[24:25], off offset:1024
	global_load_dwordx4 v[54:57], v[24:25], off offset:512
	global_load_dwordx4 v[74:77], v[22:23], off offset:1024
	global_load_dwordx4 v[58:61], v[22:23], off offset:512
	v_lshlrev_b32_e32 v24, 2, v44
	s_movk_i32 s0, 0x80
	v_bitop3_b32 v239, v24, 64, v213 bitop3:0x6c
	v_bitop3_b32 v238, v24, s0, v213 bitop3:0x6c
	v_lshrrev_b32_e32 v24, 2, v44
	v_mad_i64_i32 v[188:189], s[16:17], v21, s76, 0
	v_mad_i64_i32 v[190:191], s[16:17], v79, s76, 0
	v_mad_i64_i32 v[192:193], s[16:17], v80, s76, 0
	v_mad_i64_i32 v[194:195], s[16:17], v81, s76, 0
	v_bfe_u32 v23, v44, 2, 2
	v_and_b32_e32 v240, 12, v24
	v_add_u32_e32 v22, 0, v42
	s_and_b32 s16, s34, 0xffffff80
	v_or_b32_e32 v23, v240, v23
	s_add_i32 s17, s16, 0
	v_mad_u64_u32 v[196:197], s[34:35], v21, s77, v[22:23]
	v_mad_u64_u32 v[198:199], s[34:35], v79, s77, v[22:23]
	v_mad_u64_u32 v[200:201], s[34:35], v80, s77, v[22:23]
	v_mad_u64_u32 v[202:203], s[34:35], v81, s77, v[22:23]
	v_mul_u32_u24_e32 v22, 0x210, v23
	v_and_b32_e32 v19, 24, v19
	s_mulk_i32 s38, 0x404
	v_add3_u32 v197, s17, v22, v19
	v_or_b32_e32 v19, 0x1d0, v78
	v_add_u32_e32 v18, s17, v18
	s_add_i32 s16, s38, 0
	v_mul_u32_u24_e32 v21, 0x210, v45
	v_sub_u32_e32 v19, v19, v240
	v_ashrrev_i32_e32 v187, 31, v186
	v_ashrrev_i32_e32 v183, 31, v182
	s_add_i32 s16, s16, 0x23000
	v_add_u32_e32 v199, 0xa400, v197
	v_subrev_u32_e32 v201, s39, v19
	s_add_i32 s17, s41, s39
	v_mov_b32_e32 v181, 0xf149f2ca
	v_lshlrev_b32_e32 v204, 1, v20
	v_add_u32_e32 v203, v18, v21
	v_mov_b32_e32 v175, 0xf149f2ca
	s_mov_b64 s[34:35], s[36:37]
	v_mov_b32_e32 v78, 0
	v_mov_b32_e32 v79, v236
	v_mov_b32_e32 v80, v236
	v_mov_b32_e32 v81, v236
	v_mov_b32_e32 v94, 0
	v_mov_b32_e32 v95, v236
	v_mov_b32_e32 v96, v236
	v_mov_b32_e32 v97, v236
	v_mov_b32_e32 v42, 0
	v_mov_b32_e32 v43, v236
	v_mov_b32_e32 v44, v236
	v_mov_b32_e32 v45, v236
	v_mov_b32_e32 v90, 0
	v_mov_b32_e32 v91, v236
	v_mov_b32_e32 v92, v236
	v_mov_b32_e32 v93, v236
	v_mov_b32_e32 v18, 0
	v_mov_b32_e32 v19, v236
	v_mov_b32_e32 v20, v236
	v_mov_b32_e32 v21, v236
	v_mov_b32_e32 v82, 0
	v_mov_b32_e32 v83, v236
	v_mov_b32_e32 v84, v236
	v_mov_b32_e32 v85, v236
	v_mov_b32_e32 v22, 0
	v_mov_b32_e32 v23, v236
	v_mov_b32_e32 v24, v236
	v_mov_b32_e32 v25, v236
	v_mov_b32_e32 v86, 0
	v_mov_b32_e32 v87, v236
	v_mov_b32_e32 v88, v236
	v_mov_b32_e32 v89, v236
	v_mov_b32_e32 v184, 0
	v_mov_b32_e32 v185, v236
	s_cmp_lg_u32 s88, 0
	s_cbranch_scc0 .Lsc_pr_sc
	s_mov_b32 s95, 0
.Lsc_il_pr:
	s_cmp_ge_u32 s94, 8
	s_cbranch_scc1 .Lsc_id_pr
	s_add_i32 s72, s89, 2
	s_cmp_ge_u32 s94, s72
	s_cbranch_scc1 .Lsc_id_pr
	s_lshl_b32 s70, s94, 21
	s_mov_b32 s71, 0
	v_lshl_add_u64 v[248:249], s[70:71], 0, v[166:167]
	s_and_b32 s70, s94, 1
	s_lshl_b32 s70, s70, 12
	s_add_i32 s70, s70, s73
	s_mov_b32 s100, 0x20000
	s_mov_b32 s101, 0
	s_mov_b32 m0, s70
	s_add_i32 s70, s70, 0x100
	global_load_lds_dword v[248:249], off
	v_lshl_add_u64 v[248:249], v[248:249], 0, s[100:101]
	s_mov_b32 m0, s70
	s_add_i32 s70, s70, 0x100
	global_load_lds_dword v[248:249], off
	v_lshl_add_u64 v[248:249], v[248:249], 0, s[100:101]
	s_mov_b32 m0, s70
	s_add_i32 s70, s70, 0x100
	global_load_lds_dword v[248:249], off
	v_lshl_add_u64 v[248:249], v[248:249], 0, s[100:101]
	s_mov_b32 m0, s70
	s_add_i32 s70, s70, 0x100
	global_load_lds_dword v[248:249], off
	v_lshl_add_u64 v[248:249], v[248:249], 0, s[100:101]
	s_mov_b32 m0, s70
	s_add_i32 s70, s70, 0x100
	global_load_lds_dword v[248:249], off
	v_lshl_add_u64 v[248:249], v[248:249], 0, s[100:101]
	s_mov_b32 m0, s70
	s_add_i32 s70, s70, 0x100
	global_load_lds_dword v[248:249], off
	v_lshl_add_u64 v[248:249], v[248:249], 0, s[100:101]
	s_mov_b32 m0, s70
	s_add_i32 s70, s70, 0x100
	global_load_lds_dword v[248:249], off
	v_lshl_add_u64 v[248:249], v[248:249], 0, s[100:101]
	s_mov_b32 m0, s70
	s_add_i32 s70, s70, 0x100
	global_load_lds_dword v[248:249], off
	v_lshl_add_u64 v[248:249], v[248:249], 0, s[100:101]
	s_mov_b32 m0, s70
	s_add_i32 s70, s70, 0x100
	global_load_lds_dword v[248:249], off
	v_lshl_add_u64 v[248:249], v[248:249], 0, s[100:101]
	s_mov_b32 m0, s70
	s_add_i32 s70, s70, 0x100
	global_load_lds_dword v[248:249], off
	v_lshl_add_u64 v[248:249], v[248:249], 0, s[100:101]
	s_mov_b32 m0, s70
	s_add_i32 s70, s70, 0x100
	global_load_lds_dword v[248:249], off
	v_lshl_add_u64 v[248:249], v[248:249], 0, s[100:101]
	s_mov_b32 m0, s70
	s_add_i32 s70, s70, 0x100
	global_load_lds_dword v[248:249], off
	v_lshl_add_u64 v[248:249], v[248:249], 0, s[100:101]
	s_mov_b32 m0, s70
	s_add_i32 s70, s70, 0x100
	global_load_lds_dword v[248:249], off
	v_lshl_add_u64 v[248:249], v[248:249], 0, s[100:101]
	s_mov_b32 m0, s70
	s_add_i32 s70, s70, 0x100
	global_load_lds_dword v[248:249], off
	v_lshl_add_u64 v[248:249], v[248:249], 0, s[100:101]
	s_mov_b32 m0, s70
	s_add_i32 s70, s70, 0x100
	global_load_lds_dword v[248:249], off
	v_lshl_add_u64 v[248:249], v[248:249], 0, s[100:101]
	s_mov_b32 m0, s70
	s_add_i32 s70, s70, 0x100
	global_load_lds_dword v[248:249], off
	s_add_i32 s94, s94, 1
	s_mov_b32 s95, 1
	s_branch .Lsc_il_pr
.Lsc_id_pr:
	s_add_i32 s72, s89, 2
	s_cmp_ge_u32 s94, s72
	s_cselect_b32 s72, 1, 0
	s_and_b32 s95, s95, s72
	s_branch .Lsc_pr_end
.Lsc_pr_sc:
	s_mov_b32 s95, 0
.Lsc_pr_end:
.LBB0_36:
	s_cmp_lg_u32 s95, 0
	s_cbranch_scc1 .Lsc_w16
	s_waitcnt vmcnt(0)
	s_branch .Lsc_wd
.Lsc_w16:
	s_waitcnt vmcnt(16)
.Lsc_wd:
	s_cmp_eq_u32 s23, 8
	ds_write_b128 v196, v[58:61] offset:8192
	ds_write_b128 v196, v[74:77] offset:41984
	ds_write_b128 v198, v[54:57] offset:8192
	ds_write_b128 v198, v[70:73] offset:41984
	ds_write_b128 v200, v[50:53] offset:8192
	ds_write_b128 v200, v[66:69] offset:41984
	ds_write_b128 v202, v[46:49] offset:8192
	ds_write_b128 v202, v[62:65] offset:41984
	s_waitcnt lgkmcnt(0)
	s_barrier
	s_cbranch_scc1 .LBB0_38
	s_mul_i32 s38, s17, 0x1600
	s_mul_hi_i32 s39, s17, 0x1600
	s_add_u32 s38, s15, s38
	s_addc_u32 s39, s40, s39
	v_lshl_add_u64 v[46:47], s[38:39], 0, v[188:189]
	v_mov_b32_e32 v205, v163
	v_lshl_add_u64 v[46:47], v[46:47], 0, v[204:205]
	global_load_dwordx4 v[58:61], v[46:47], off offset:512
	global_load_dwordx4 v[74:77], v[46:47], off offset:1024
	v_lshl_add_u64 v[46:47], s[38:39], 0, v[190:191]
	v_lshl_add_u64 v[46:47], v[46:47], 0, v[204:205]
	global_load_dwordx4 v[54:57], v[46:47], off offset:512
	global_load_dwordx4 v[70:73], v[46:47], off offset:1024
	v_lshl_add_u64 v[46:47], s[38:39], 0, v[192:193]
	v_lshl_add_u64 v[46:47], v[46:47], 0, v[204:205]
	global_load_dwordx4 v[50:53], v[46:47], off offset:512
	global_load_dwordx4 v[66:69], v[46:47], off offset:1024
	v_lshl_add_u64 v[46:47], s[38:39], 0, v[194:195]
	v_lshl_add_u64 v[62:63], v[46:47], 0, v[204:205]
	global_load_dwordx4 v[46:49], v[62:63], off offset:512
	s_nop 0
	global_load_dwordx4 v[62:65], v[62:63], off offset:1024
.LBB0_38:
	s_cmp_lg_u32 s88, 0
	s_cbranch_scc1 .Lsc_nodec
	s_cmp_ge_u32 s89, 8
	s_cbranch_scc1 .Lsc_nodec
	v_and_b32_e32 v241, 15, v229
	s_lshl_b32 s70, s89, 4
	v_add_u32_e32 v241, s70, v241
	v_lshlrev_b32_e32 v241, 5, v241
	global_load_dword v241, v241, s[58:59]
.Lsc_nodec:
	ds_read_b128 v[98:101], v203 offset:8192
	ds_read_b128 v[102:105], v203 offset:8256
	ds_read_b128 v[110:113], v203 offset:25088
	ds_read_b128 v[130:133], v203 offset:33536
	s_mov_b64 s[38:39], -1
	s_waitcnt lgkmcnt(3)
	v_mfma_f32_16x16x32_bf16 v[106:109], v[98:101], v[26:29], 0
	s_cmp_lt_i32 s23, 6
	v_mfma_f32_16x16x32_bf16 v[98:101], v[98:101], v[34:37], 0
	s_waitcnt lgkmcnt(2)
	v_mfma_f32_16x16x32_bf16 v[126:129], v[102:105], v[30:33], v[106:109]
	s_nop 3
	ds_read_b128 v[106:109], v203 offset:16640
	v_mfma_f32_16x16x32_bf16 v[122:125], v[102:105], v[38:41], v[98:101]
	s_nop 2
	ds_read_b128 v[98:101], v203 offset:16704
	s_waitcnt lgkmcnt(1)
	v_mfma_f32_16x16x32_bf16 v[102:105], v[106:109], v[26:29], 0
	s_waitcnt lgkmcnt(0)
	v_mfma_f32_16x16x32_bf16 v[114:117], v[98:101], v[30:33], v[102:105]
	v_mfma_f32_16x16x32_bf16 v[102:105], v[106:109], v[34:37], 0
	v_mfma_f32_16x16x32_bf16 v[118:121], v[98:101], v[38:41], v[102:105]
	ds_read_b128 v[98:101], v203 offset:25152
	v_mfma_f32_16x16x32_bf16 v[102:105], v[110:113], v[26:29], 0
	s_waitcnt lgkmcnt(0)
	v_mfma_f32_16x16x32_bf16 v[106:109], v[98:101], v[30:33], v[102:105]
	v_mfma_f32_16x16x32_bf16 v[102:105], v[110:113], v[34:37], 0
	v_mfma_f32_16x16x32_bf16 v[110:113], v[98:101], v[38:41], v[102:105]
	s_nop 6
	ds_read_b128 v[102:105], v203 offset:33600
	v_mfma_f32_16x16x32_bf16 v[98:101], v[130:133], v[26:29], 0
	v_mfma_f32_16x16x32_bf16 v[130:133], v[130:133], v[34:37], 0
	s_waitcnt lgkmcnt(0)
	v_mfma_f32_16x16x32_bf16 v[98:101], v[102:105], v[30:33], v[98:101]
	v_mfma_f32_16x16x32_bf16 v[102:105], v[102:105], v[38:41], v[130:133]
	s_cbranch_scc0 .LBB0_96
	s_nop 3
	v_mov_b32_e32 v130, s16
	ds_read_b32 v136, v130 offset:1024
	s_waitcnt lgkmcnt(0)
	v_mov_b64_e32 v[140:141], v[138:139]
	s_mov_b64 s[38:39], 0
	v_mov_b64_e32 v[138:139], v[136:137]
	s_branch .LBB0_97

.LBB0_99:
	s_waitcnt lgkmcnt(14)
	v_pk_add_f32 v[126:127], v[126:127], v[132:133]
	s_waitcnt lgkmcnt(2)
	v_mov_b32_e32 v139, v136
	v_pk_add_f32 v[214:215], v[128:129], v[140:141]
	v_pk_add_f32 v[114:115], v[114:115], v[142:143]
	v_pk_add_f32 v[142:143], v[110:111], v[154:155]
	v_pk_add_f32 v[110:111], v[100:101], v[206:207]
	v_pk_add_f32 v[100:101], v[102:103], v[138:139]
	v_max3_f32 v102, v126, s10, v127
	v_max3_f32 v102, v102, v214, v215
	v_pk_add_f32 v[116:117], v[116:117], v[156:157]
	v_max3_f32 v102, v102, v114, v115
	v_pk_add_f32 v[128:129], v[124:125], v[134:135]
	v_pk_add_f32 v[134:135], v[118:119], v[146:147]
	v_pk_add_f32 v[118:119], v[106:107], v[150:151]
	v_max3_f32 v102, v102, v116, v117
	v_pk_add_f32 v[108:109], v[108:109], v[160:161]
	v_max3_f32 v102, v102, v118, v119
	v_pk_add_f32 v[140:141], v[112:113], v[148:149]
	v_pk_add_f32 v[112:113], v[98:99], v[158:159]
	v_max3_f32 v102, v102, v108, v109
	v_max3_f32 v102, v102, v112, v113
	v_max3_f32 v102, v102, v110, v111
	ds_bpermute_b32 v103, v239, v102
	v_pk_add_f32 v[132:133], v[120:121], v[144:145]
	v_pk_add_f32 v[130:131], v[122:123], v[130:131]
	s_waitcnt lgkmcnt(1)
	v_pk_add_f32 v[98:99], v[104:105], v[152:153]
	ds_read_b64_tr_b16 v[156:157], v197 offset:50432
	ds_read_b64_tr_b16 v[154:155], v197 offset:41984
	ds_read_b64_tr_b16 v[158:159], v197 offset:42016
	s_waitcnt lgkmcnt(3)
	v_max_f32_e32 v103, v103, v103
	v_max_f32_e32 v102, v102, v103
	ds_bpermute_b32 v103, v238, v102
	s_waitcnt lgkmcnt(0)
	v_max3_f32 v138, v181, v102, v103
	v_sub_f32_e32 v103, v126, v138
	v_exp_f32_e32 v107, v103
	v_sub_f32_e32 v103, v127, v138
	v_exp_f32_e32 v139, v103
	v_sub_f32_e32 v103, v214, v138
	v_exp_f32_e32 v144, v103
	v_sub_f32_e32 v103, v215, v138
	v_exp_f32_e32 v145, v103
	v_sub_f32_e32 v103, v114, v138
	v_exp_f32_e32 v146, v103
	v_sub_f32_e32 v103, v115, v138
	v_exp_f32_e32 v147, v103
	v_sub_f32_e32 v103, v116, v138
	v_sub_f32_e32 v102, v181, v138
	v_exp_f32_e32 v126, v103
	v_sub_f32_e32 v103, v117, v138
	v_exp_f32_e32 v124, v103
	v_sub_f32_e32 v103, v118, v138
	v_exp_f32_e32 v106, v102
	v_max3_f32 v102, v130, s10, v131
	v_exp_f32_e32 v122, v103
	v_sub_f32_e32 v103, v119, v138
	v_max3_f32 v102, v102, v128, v129
	v_exp_f32_e32 v120, v103
	v_sub_f32_e32 v103, v108, v138
	v_max3_f32 v102, v102, v134, v135
	v_exp_f32_e32 v118, v103
	v_sub_f32_e32 v103, v109, v138
	v_max3_f32 v102, v102, v132, v133
	v_exp_f32_e32 v116, v103
	v_sub_f32_e32 v103, v112, v138
	v_max3_f32 v102, v102, v142, v143
	v_exp_f32_e32 v114, v103
	v_sub_f32_e32 v103, v113, v138
	v_max3_f32 v102, v102, v140, v141
	v_exp_f32_e32 v112, v103
	v_sub_f32_e32 v103, v110, v138
	v_max3_f32 v102, v102, v100, v101
	v_exp_f32_e32 v110, v103
	v_sub_f32_e32 v103, v111, v138
	v_max3_f32 v102, v102, v98, v99
	v_exp_f32_e32 v108, v103
	ds_bpermute_b32 v103, v239, v102
	v_pk_mul_f32 v[88:89], v[88:89], v[106:107] op_sel_hi:[1,0]
	v_pk_mul_f32 v[86:87], v[86:87], v[106:107] op_sel_hi:[1,0]
	v_pk_mul_f32 v[92:93], v[92:93], v[106:107] op_sel_hi:[1,0]
	v_pk_mul_f32 v[90:91], v[90:91], v[106:107] op_sel_hi:[1,0]
	s_waitcnt lgkmcnt(0)
	v_max_f32_e32 v103, v103, v103
	v_max_f32_e32 v102, v102, v103
	ds_bpermute_b32 v103, v238, v102
	v_pk_mul_f32 v[84:85], v[84:85], v[106:107] op_sel_hi:[1,0]
	v_pk_mul_f32 v[82:83], v[82:83], v[106:107] op_sel_hi:[1,0]
	v_pk_mul_f32 v[96:97], v[96:97], v[106:107] op_sel_hi:[1,0]
	v_pk_mul_f32 v[94:95], v[94:95], v[106:107] op_sel_hi:[1,0]
	s_waitcnt lgkmcnt(0)
	v_max3_f32 v148, v175, v102, v103
	v_sub_f32_e32 v103, v130, v148
	v_exp_f32_e32 v149, v103
	v_sub_f32_e32 v103, v131, v148
	v_exp_f32_e32 v150, v103
	v_sub_f32_e32 v103, v128, v148
	v_exp_f32_e32 v151, v103
	v_sub_f32_e32 v103, v129, v148
	v_exp_f32_e32 v129, v103
	v_sub_f32_e32 v103, v134, v148
	v_exp_f32_e32 v152, v103
	v_sub_f32_e32 v103, v135, v148
	v_exp_f32_e32 v153, v103
	v_sub_f32_e32 v103, v132, v148
	v_sub_f32_e32 v102, v175, v148
	v_exp_f32_e32 v127, v103
	v_sub_f32_e32 v103, v133, v148
	v_exp_f32_e32 v125, v103
	v_sub_f32_e32 v103, v142, v148
	v_exp_f32_e32 v128, v102
	v_exp_f32_e32 v123, v103
	v_sub_f32_e32 v103, v143, v148
	v_exp_f32_e32 v121, v103
	v_sub_f32_e32 v103, v140, v148
	v_sub_f32_e32 v100, v100, v148
	v_sub_f32_e32 v98, v98, v148
	v_exp_f32_e32 v119, v103
	v_sub_f32_e32 v103, v141, v148
	v_exp_f32_e32 v115, v100
	v_sub_f32_e32 v100, v101, v148
	v_exp_f32_e32 v111, v98
	v_sub_f32_e32 v98, v99, v148
	v_exp_f32_e32 v117, v103
	v_exp_f32_e32 v113, v100
	v_exp_f32_e32 v109, v98
	v_pk_mul_f32 v[24:25], v[24:25], v[128:129] op_sel_hi:[1,0]
	v_pk_mul_f32 v[22:23], v[22:23], v[128:129] op_sel_hi:[1,0]
	v_cvt_pk_bf16_f32 v130, v107, v139
	v_cvt_pk_bf16_f32 v131, v144, v145
	v_cvt_pk_bf16_f32 v132, v146, v147
	v_cvt_pk_bf16_f32 v133, v126, v124
	v_cvt_pk_bf16_f32 v140, v149, v150
	v_cvt_pk_bf16_f32 v141, v151, v129
	v_cvt_pk_bf16_f32 v142, v152, v153
	v_cvt_pk_bf16_f32 v143, v127, v125
	v_mfma_f32_16x16x32_bf16 v[86:89], v[154:157], v[130:133], v[86:89]
	v_mul_f32_e64 v104, v80, v128
	v_mul_f32_e64 v105, v81, v128
	v_pk_mul_f32 v[102:103], v[78:79], v[128:129] op_sel_hi:[1,0]
	v_cvt_pk_bf16_f32 v78, v122, v120
	v_mfma_f32_16x16x32_bf16 v[22:25], v[154:157], v[140:143], v[22:25]
	ds_read_b64_tr_b16 v[154:155], v197 offset:58880
	ds_read_b64_tr_b16 v[156:157], v199 offset:25344
	ds_read_b64_tr_b16 v[244:245], v199 offset:25376
	v_cvt_pk_bf16_f32 v79, v118, v116
	v_cvt_pk_bf16_f32 v80, v114, v112
	v_cvt_pk_bf16_f32 v81, v110, v108
	v_cvt_pk_bf16_f32 v98, v123, v121
	v_cvt_pk_bf16_f32 v99, v119, v117
	v_cvt_pk_bf16_f32 v100, v115, v113
	v_cvt_pk_bf16_f32 v101, v111, v109
	s_waitcnt lgkmcnt(1)
	v_mfma_f32_16x16x32_bf16 v[86:89], v[154:157], v[78:81], v[86:89]
	ds_read_b64_tr_b16 v[160:161], v197 offset:50464
	ds_read_b64_tr_b16 v[242:243], v197 offset:58912
	v_pk_mul_f32 v[44:45], v[44:45], v[128:129] op_sel_hi:[1,0]
	v_mfma_f32_16x16x32_bf16 v[22:25], v[154:157], v[98:101], v[22:25]
	ds_read_b64_tr_b16 v[154:155], v197 offset:42048
	ds_read_b64_tr_b16 v[156:157], v197 offset:50496
	v_pk_mul_f32 v[42:43], v[42:43], v[128:129] op_sel_hi:[1,0]
	v_pk_mul_f32 v[20:21], v[20:21], v[128:129] op_sel_hi:[1,0]
	s_waitcnt lgkmcnt(0)
	v_mfma_f32_16x16x32_bf16 v[90:93], v[154:157], v[130:133], v[90:93]
	v_mul_f32_e64 v18, v18, v128
	v_mul_f32_e64 v19, v19, v128
	v_mfma_f32_16x16x32_bf16 v[42:45], v[154:157], v[140:143], v[42:45]
	ds_read_b64_tr_b16 v[154:155], v197 offset:58944
	ds_read_b64_tr_b16 v[156:157], v199 offset:25408
	s_waitcnt lgkmcnt(0)
	v_mfma_f32_16x16x32_bf16 v[90:93], v[154:157], v[78:81], v[90:93]
	v_mfma_f32_16x16x32_bf16 v[42:45], v[154:157], v[98:101], v[42:45]
	ds_read_b64_tr_b16 v[154:155], v197 offset:42080
	ds_read_b64_tr_b16 v[156:157], v197 offset:50528
	v_mfma_f32_16x16x32_bf16 v[82:85], v[158:161], v[130:133], v[82:85]
	s_waitcnt lgkmcnt(0)
	v_mfma_f32_16x16x32_bf16 v[94:97], v[154:157], v[130:133], v[94:97]
	ds_read_b64_tr_b16 v[130:131], v197 offset:58976
	ds_read_b64_tr_b16 v[132:133], v199 offset:25440
	v_mfma_f32_16x16x32_bf16 v[18:21], v[158:161], v[140:143], v[18:21]
	v_mfma_f32_16x16x32_bf16 v[102:105], v[154:157], v[140:143], v[102:105]
	v_mfma_f32_16x16x32_bf16 v[82:85], v[242:245], v[78:81], v[82:85]
	v_mfma_f32_16x16x32_bf16 v[18:21], v[242:245], v[98:101], v[18:21]
	s_waitcnt lgkmcnt(0)
	v_mfma_f32_16x16x32_bf16 v[94:97], v[130:133], v[78:81], v[94:97]
	v_mfma_f32_16x16x32_bf16 v[78:81], v[130:133], v[98:101], v[102:105]
	s_cmp_lg_u32 s88, 0
	s_cbranch_scc1 .Lsc_noscan
	s_waitcnt vmcnt(0)
	s_cmp_ge_u32 s89, 8
	s_cbranch_scc1 .Lsc_noscan
	s_and_b32 s70, s89, 1
	s_lshl_b32 s70, s70, 12
	v_add_u32_e32 v247, s70, v246
	ds_read_b32 v2, v247
	ds_read_b32 v3, v247 offset:256
	ds_read_b32 v4, v247 offset:512
	ds_read_b32 v5, v247 offset:768
	ds_read_b32 v6, v247 offset:1024
	ds_read_b32 v7, v247 offset:1280
	ds_read_b32 v8, v247 offset:1536
	ds_read_b32 v9, v247 offset:1792
	ds_read_b32 v10, v247 offset:2048
	ds_read_b32 v11, v247 offset:2304
	ds_read_b32 v12, v247 offset:2560
	ds_read_b32 v13, v247 offset:2816
	ds_read_b32 v14, v247 offset:3072
	ds_read_b32 v15, v247 offset:3328
	ds_read_b32 v16, v247 offset:3584
	ds_read_b32 v17, v247 offset:3840
	s_lshl_b32 s70, s89, 21
	s_mov_b32 s71, 0
	v_lshl_add_u64 v[98:99], s[70:71], 0, v[166:167]
	s_mov_b32 s100, 0x20000
	s_mov_b32 s101, 0
	s_waitcnt lgkmcnt(0)
	v_readlane_b32 s70, v241, 0
	v_cvt_pk_bf16_f32 v100, v177, v176
	global_store_dword v[98:99], v100, off
	v_lshlrev_b32_e32 v101, 16, v2
	v_and_b32_e32 v102, 0xffff0000, v2
	v_readlane_b32 s71, v241, 1
	v_fma_f32 v177, v177, s70, v101
	v_fma_f32 v176, v176, s70, v102
	v_lshl_add_u64 v[98:99], v[98:99], 0, s[100:101]
	v_cvt_pk_bf16_f32 v100, v177, v176
	global_store_dword v[98:99], v100, off
	v_lshlrev_b32_e32 v101, 16, v3
	v_and_b32_e32 v102, 0xffff0000, v3
	v_readlane_b32 s70, v241, 2
	v_fma_f32 v177, v177, s71, v101
	v_fma_f32 v176, v176, s71, v102
	v_lshl_add_u64 v[98:99], v[98:99], 0, s[100:101]
	v_cvt_pk_bf16_f32 v100, v177, v176
	global_store_dword v[98:99], v100, off
	v_lshlrev_b32_e32 v101, 16, v4
	v_and_b32_e32 v102, 0xffff0000, v4
	v_readlane_b32 s71, v241, 3
	v_fma_f32 v177, v177, s70, v101
	v_fma_f32 v176, v176, s70, v102
	v_lshl_add_u64 v[98:99], v[98:99], 0, s[100:101]
	v_cvt_pk_bf16_f32 v100, v177, v176
	global_store_dword v[98:99], v100, off
	v_lshlrev_b32_e32 v101, 16, v5
	v_and_b32_e32 v102, 0xffff0000, v5
	v_readlane_b32 s70, v241, 4
	v_fma_f32 v177, v177, s71, v101
	v_fma_f32 v176, v176, s71, v102
	v_lshl_add_u64 v[98:99], v[98:99], 0, s[100:101]
	v_cvt_pk_bf16_f32 v100, v177, v176
	global_store_dword v[98:99], v100, off
	v_lshlrev_b32_e32 v101, 16, v6
	v_and_b32_e32 v102, 0xffff0000, v6
	v_readlane_b32 s71, v241, 5
	v_fma_f32 v177, v177, s70, v101
	v_fma_f32 v176, v176, s70, v102
	v_lshl_add_u64 v[98:99], v[98:99], 0, s[100:101]
	v_cvt_pk_bf16_f32 v100, v177, v176
	global_store_dword v[98:99], v100, off
	v_lshlrev_b32_e32 v101, 16, v7
	v_and_b32_e32 v102, 0xffff0000, v7
	v_readlane_b32 s70, v241, 6
	v_fma_f32 v177, v177, s71, v101
	v_fma_f32 v176, v176, s71, v102
	v_lshl_add_u64 v[98:99], v[98:99], 0, s[100:101]
	v_cvt_pk_bf16_f32 v100, v177, v176
	global_store_dword v[98:99], v100, off
	v_lshlrev_b32_e32 v101, 16, v8
	v_and_b32_e32 v102, 0xffff0000, v8
	v_readlane_b32 s71, v241, 7
	v_fma_f32 v177, v177, s70, v101
	v_fma_f32 v176, v176, s70, v102
	v_lshl_add_u64 v[98:99], v[98:99], 0, s[100:101]
	v_cvt_pk_bf16_f32 v100, v177, v176
	global_store_dword v[98:99], v100, off
	v_lshlrev_b32_e32 v101, 16, v9
	v_and_b32_e32 v102, 0xffff0000, v9
	v_readlane_b32 s70, v241, 8
	v_fma_f32 v177, v177, s71, v101
	v_fma_f32 v176, v176, s71, v102
	v_lshl_add_u64 v[98:99], v[98:99], 0, s[100:101]
	v_cvt_pk_bf16_f32 v100, v177, v176
	global_store_dword v[98:99], v100, off
	v_lshlrev_b32_e32 v101, 16, v10
	v_and_b32_e32 v102, 0xffff0000, v10
	v_readlane_b32 s71, v241, 9
	v_fma_f32 v177, v177, s70, v101
	v_fma_f32 v176, v176, s70, v102
	v_lshl_add_u64 v[98:99], v[98:99], 0, s[100:101]
	v_cvt_pk_bf16_f32 v100, v177, v176
	global_store_dword v[98:99], v100, off
	v_lshlrev_b32_e32 v101, 16, v11
	v_and_b32_e32 v102, 0xffff0000, v11
	v_readlane_b32 s70, v241, 10
	v_fma_f32 v177, v177, s71, v101
	v_fma_f32 v176, v176, s71, v102
	v_lshl_add_u64 v[98:99], v[98:99], 0, s[100:101]
	v_cvt_pk_bf16_f32 v100, v177, v176
	global_store_dword v[98:99], v100, off
	v_lshlrev_b32_e32 v101, 16, v12
	v_and_b32_e32 v102, 0xffff0000, v12
	v_readlane_b32 s71, v241, 11
	v_fma_f32 v177, v177, s70, v101
	v_fma_f32 v176, v176, s70, v102
	v_lshl_add_u64 v[98:99], v[98:99], 0, s[100:101]
	v_cvt_pk_bf16_f32 v100, v177, v176
	global_store_dword v[98:99], v100, off
	v_lshlrev_b32_e32 v101, 16, v13
	v_and_b32_e32 v102, 0xffff0000, v13
	v_readlane_b32 s70, v241, 12
	v_fma_f32 v177, v177, s71, v101
	v_fma_f32 v176, v176, s71, v102
	v_lshl_add_u64 v[98:99], v[98:99], 0, s[100:101]
	v_cvt_pk_bf16_f32 v100, v177, v176
	global_store_dword v[98:99], v100, off
	v_lshlrev_b32_e32 v101, 16, v14
	v_and_b32_e32 v102, 0xffff0000, v14
	v_readlane_b32 s71, v241, 13
	v_fma_f32 v177, v177, s70, v101
	v_fma_f32 v176, v176, s70, v102
	v_lshl_add_u64 v[98:99], v[98:99], 0, s[100:101]
	v_cvt_pk_bf16_f32 v100, v177, v176
	global_store_dword v[98:99], v100, off
	v_lshlrev_b32_e32 v101, 16, v15
	v_and_b32_e32 v102, 0xffff0000, v15
	v_readlane_b32 s70, v241, 14
	v_fma_f32 v177, v177, s71, v101
	v_fma_f32 v176, v176, s71, v102
	v_lshl_add_u64 v[98:99], v[98:99], 0, s[100:101]
	v_cvt_pk_bf16_f32 v100, v177, v176
	global_store_dword v[98:99], v100, off
	v_lshlrev_b32_e32 v101, 16, v16
	v_and_b32_e32 v102, 0xffff0000, v16
	v_readlane_b32 s71, v241, 15
	v_fma_f32 v177, v177, s70, v101
	v_fma_f32 v176, v176, s70, v102
	v_lshl_add_u64 v[98:99], v[98:99], 0, s[100:101]
	v_cvt_pk_bf16_f32 v100, v177, v176
	global_store_dword v[98:99], v100, off
	v_lshlrev_b32_e32 v101, 16, v17
	v_and_b32_e32 v102, 0xffff0000, v17
	v_fma_f32 v177, v177, s71, v101
	v_fma_f32 v176, v176, s71, v102
.Lsc_noscan:
	s_add_i32 s89, s89, 1
	v_add_f32_e32 v98, 0, v107
	v_add_f32_e32 v99, 0, v149
	v_add_f32_e32 v98, v139, v98
	v_add_f32_e32 v99, v150, v99
	v_add_f32_e32 v98, v144, v98
	v_add_f32_e32 v99, v151, v99
	v_add_f32_e32 v98, v145, v98
	v_add_f32_e32 v99, v129, v99
	v_add_f32_e32 v98, v146, v98
	v_add_f32_e32 v99, v152, v99
	v_add_f32_e32 v98, v147, v98
	v_add_f32_e32 v99, v153, v99
	v_pk_add_f32 v[98:99], v[126:127], v[98:99]
	s_andn2_b64 s[36:37], s[36:37], exec
	v_pk_add_f32 v[98:99], v[124:125], v[98:99]
	s_and_b64 s[50:51], s[34:35], exec
	v_pk_add_f32 v[98:99], v[122:123], v[98:99]
	v_mov_b32_e32 v107, v128
	v_pk_add_f32 v[98:99], v[120:121], v[98:99]
	s_add_i32 s38, s23, 1
	v_pk_add_f32 v[98:99], v[118:119], v[98:99]
	s_add_i32 s17, s17, 64
	v_pk_add_f32 v[98:99], v[116:117], v[98:99]
	s_or_b64 s[36:37], s[36:37], s[50:51]
	v_pk_add_f32 v[98:99], v[114:115], v[98:99]
	s_cmp_gt_i32 s23, 7
	v_pk_add_f32 v[98:99], v[112:113], v[98:99]
	v_subrev_u32_e32 v201, 64, v201
	v_pk_add_f32 v[98:99], v[110:111], v[98:99]
	s_nop 0
	v_pk_add_f32 v[98:99], v[108:109], v[98:99]
	s_barrier
	v_pk_fma_f32 v[184:185], v[184:185], v[106:107], v[98:99]
	s_cbranch_scc1 .LBB0_34
	v_mov_b32_e32 v181, v138
	v_mov_b32_e32 v175, v148
	s_mov_b32 s23, s38
	s_cmp_lg_u32 s88, 0
	s_cbranch_scc0 .Lsc_tl_sc
	s_mov_b32 s95, 0
	s_cmp_ge_u32 s94, 8
	s_cbranch_scc1 .LBB0_36
	s_lshl_b32 s70, s94, 21
	s_mov_b32 s71, 0
	v_lshl_add_u64 v[248:249], s[70:71], 0, v[166:167]
	s_and_b32 s70, s94, 1
	s_lshl_b32 s70, s70, 12
	s_add_i32 s70, s70, s73
	s_mov_b32 s100, 0x20000
	s_mov_b32 s101, 0
	s_mov_b32 m0, s70
	s_add_i32 s70, s70, 0x100
	global_load_lds_dword v[248:249], off
	v_lshl_add_u64 v[248:249], v[248:249], 0, s[100:101]
	s_mov_b32 m0, s70
	s_add_i32 s70, s70, 0x100
	global_load_lds_dword v[248:249], off
	v_lshl_add_u64 v[248:249], v[248:249], 0, s[100:101]
	s_mov_b32 m0, s70
	s_add_i32 s70, s70, 0x100
	global_load_lds_dword v[248:249], off
	v_lshl_add_u64 v[248:249], v[248:249], 0, s[100:101]
	s_mov_b32 m0, s70
	s_add_i32 s70, s70, 0x100
	global_load_lds_dword v[248:249], off
	v_lshl_add_u64 v[248:249], v[248:249], 0, s[100:101]
	s_mov_b32 m0, s70
	s_add_i32 s70, s70, 0x100
	global_load_lds_dword v[248:249], off
	v_lshl_add_u64 v[248:249], v[248:249], 0, s[100:101]
	s_mov_b32 m0, s70
	s_add_i32 s70, s70, 0x100
	global_load_lds_dword v[248:249], off
	v_lshl_add_u64 v[248:249], v[248:249], 0, s[100:101]
	s_mov_b32 m0, s70
	s_add_i32 s70, s70, 0x100
	global_load_lds_dword v[248:249], off
	v_lshl_add_u64 v[248:249], v[248:249], 0, s[100:101]
	s_mov_b32 m0, s70
	s_add_i32 s70, s70, 0x100
	global_load_lds_dword v[248:249], off
	v_lshl_add_u64 v[248:249], v[248:249], 0, s[100:101]
	s_mov_b32 m0, s70
	s_add_i32 s70, s70, 0x100
	global_load_lds_dword v[248:249], off
	v_lshl_add_u64 v[248:249], v[248:249], 0, s[100:101]
	s_mov_b32 m0, s70
	s_add_i32 s70, s70, 0x100
	global_load_lds_dword v[248:249], off
	v_lshl_add_u64 v[248:249], v[248:249], 0, s[100:101]
	s_mov_b32 m0, s70
	s_add_i32 s70, s70, 0x100
	global_load_lds_dword v[248:249], off
	v_lshl_add_u64 v[248:249], v[248:249], 0, s[100:101]
	s_mov_b32 m0, s70
	s_add_i32 s70, s70, 0x100
	global_load_lds_dword v[248:249], off
	v_lshl_add_u64 v[248:249], v[248:249], 0, s[100:101]
	s_mov_b32 m0, s70
	s_add_i32 s70, s70, 0x100
	global_load_lds_dword v[248:249], off
	v_lshl_add_u64 v[248:249], v[248:249], 0, s[100:101]
	s_mov_b32 m0, s70
	s_add_i32 s70, s70, 0x100
	global_load_lds_dword v[248:249], off
	v_lshl_add_u64 v[248:249], v[248:249], 0, s[100:101]
	s_mov_b32 m0, s70
	s_add_i32 s70, s70, 0x100
	global_load_lds_dword v[248:249], off
	v_lshl_add_u64 v[248:249], v[248:249], 0, s[100:101]
	s_mov_b32 m0, s70
	s_add_i32 s70, s70, 0x100
	global_load_lds_dword v[248:249], off
	s_add_i32 s94, s94, 1
	s_add_i32 s72, s89, 2
	s_cmp_ge_u32 s94, s72
	s_cselect_b32 s95, 1, 0
	s_branch .LBB0_36
.Lsc_tl_sc:
	s_mov_b32 s95, 1
	s_branch .LBB0_36

.LBB0_146:
.Lsc_lo_loop:
	s_cmp_ge_u32 s89, 8
	s_cbranch_scc1 .Lsc_lo_done
	s_cmp_lg_u32 s88, 0
	s_cbranch_scc0 .Lsc_lo_b1
	s_mov_b32 s95, 0

.Lsc_id_lo:
	s_add_i32 s72, s89, 2
	s_cmp_ge_u32 s94, s72
	s_cselect_b32 s72, 1, 0
	s_and_b32 s95, s95, s72
	s_cmp_lg_u32 s95, 0
	s_cbranch_scc1 .Lsc_lo_w16
	s_add_i32 s72, s89, 2
	s_cmp_ge_u32 s94, s72
	s_cbranch_scc1 .Lsc_lo_w16
	s_waitcnt vmcnt(0)
	s_branch .Lsc_lo_b1

.Lsc_lo_b1:
	s_barrier
	s_cmp_lg_u32 s88, 0
	s_cbranch_scc1 .Lsc_lo_b2
	v_and_b32_e32 v241, 15, v229
	s_lshl_b32 s70, s89, 4
	v_add_u32_e32 v241, s70, v241
	v_lshlrev_b32_e32 v241, 5, v241
	global_load_dword v241, v241, s[58:59]
	s_waitcnt vmcnt(0)
	s_and_b32 s70, s89, 1
	s_lshl_b32 s70, s70, 12
	v_add_u32_e32 v247, s70, v246
	ds_read_b32 v2, v247
	ds_read_b32 v3, v247 offset:256
	ds_read_b32 v4, v247 offset:512
	ds_read_b32 v5, v247 offset:768
	ds_read_b32 v6, v247 offset:1024
	ds_read_b32 v7, v247 offset:1280
	ds_read_b32 v8, v247 offset:1536
	ds_read_b32 v9, v247 offset:1792
	ds_read_b32 v10, v247 offset:2048
	ds_read_b32 v11, v247 offset:2304
	ds_read_b32 v12, v247 offset:2560
	ds_read_b32 v13, v247 offset:2816
	ds_read_b32 v14, v247 offset:3072
	ds_read_b32 v15, v247 offset:3328
	ds_read_b32 v16, v247 offset:3584
	ds_read_b32 v17, v247 offset:3840
	s_lshl_b32 s70, s89, 21
	s_mov_b32 s71, 0
	v_lshl_add_u64 v[98:99], s[70:71], 0, v[166:167]
	s_mov_b32 s100, 0x20000
	s_mov_b32 s101, 0
	s_waitcnt lgkmcnt(0)
	v_readlane_b32 s70, v241, 0
	v_cvt_pk_bf16_f32 v100, v177, v176
	global_store_dword v[98:99], v100, off
	v_lshlrev_b32_e32 v101, 16, v2
	v_and_b32_e32 v102, 0xffff0000, v2
	v_readlane_b32 s71, v241, 1
	v_fma_f32 v177, v177, s70, v101
	v_fma_f32 v176, v176, s70, v102
	v_lshl_add_u64 v[98:99], v[98:99], 0, s[100:101]
	v_cvt_pk_bf16_f32 v100, v177, v176
	global_store_dword v[98:99], v100, off
	v_lshlrev_b32_e32 v101, 16, v3
	v_and_b32_e32 v102, 0xffff0000, v3
	v_readlane_b32 s70, v241, 2
	v_fma_f32 v177, v177, s71, v101
	v_fma_f32 v176, v176, s71, v102
	v_lshl_add_u64 v[98:99], v[98:99], 0, s[100:101]
	v_cvt_pk_bf16_f32 v100, v177, v176
	global_store_dword v[98:99], v100, off
	v_lshlrev_b32_e32 v101, 16, v4
	v_and_b32_e32 v102, 0xffff0000, v4
	v_readlane_b32 s71, v241, 3
	v_fma_f32 v177, v177, s70, v101
	v_fma_f32 v176, v176, s70, v102
	v_lshl_add_u64 v[98:99], v[98:99], 0, s[100:101]
	v_cvt_pk_bf16_f32 v100, v177, v176
	global_store_dword v[98:99], v100, off
	v_lshlrev_b32_e32 v101, 16, v5
	v_and_b32_e32 v102, 0xffff0000, v5
	v_readlane_b32 s70, v241, 4
	v_fma_f32 v177, v177, s71, v101
	v_fma_f32 v176, v176, s71, v102
	v_lshl_add_u64 v[98:99], v[98:99], 0, s[100:101]
	v_cvt_pk_bf16_f32 v100, v177, v176
	global_store_dword v[98:99], v100, off
	v_lshlrev_b32_e32 v101, 16, v6
	v_and_b32_e32 v102, 0xffff0000, v6
	v_readlane_b32 s71, v241, 5
	v_fma_f32 v177, v177, s70, v101
	v_fma_f32 v176, v176, s70, v102
	v_lshl_add_u64 v[98:99], v[98:99], 0, s[100:101]
	v_cvt_pk_bf16_f32 v100, v177, v176
	global_store_dword v[98:99], v100, off
	v_lshlrev_b32_e32 v101, 16, v7
	v_and_b32_e32 v102, 0xffff0000, v7
	v_readlane_b32 s70, v241, 6
	v_fma_f32 v177, v177, s71, v101
	v_fma_f32 v176, v176, s71, v102
	v_lshl_add_u64 v[98:99], v[98:99], 0, s[100:101]
	v_cvt_pk_bf16_f32 v100, v177, v176
	global_store_dword v[98:99], v100, off
	v_lshlrev_b32_e32 v101, 16, v8
	v_and_b32_e32 v102, 0xffff0000, v8
	v_readlane_b32 s71, v241, 7
	v_fma_f32 v177, v177, s70, v101
	v_fma_f32 v176, v176, s70, v102
	v_lshl_add_u64 v[98:99], v[98:99], 0, s[100:101]
	v_cvt_pk_bf16_f32 v100, v177, v176
	global_store_dword v[98:99], v100, off
	v_lshlrev_b32_e32 v101, 16, v9
	v_and_b32_e32 v102, 0xffff0000, v9
	v_readlane_b32 s70, v241, 8
	v_fma_f32 v177, v177, s71, v101
	v_fma_f32 v176, v176, s71, v102
	v_lshl_add_u64 v[98:99], v[98:99], 0, s[100:101]
	v_cvt_pk_bf16_f32 v100, v177, v176
	global_store_dword v[98:99], v100, off
	v_lshlrev_b32_e32 v101, 16, v10
	v_and_b32_e32 v102, 0xffff0000, v10
	v_readlane_b32 s71, v241, 9
	v_fma_f32 v177, v177, s70, v101
	v_fma_f32 v176, v176, s70, v102
	v_lshl_add_u64 v[98:99], v[98:99], 0, s[100:101]
	v_cvt_pk_bf16_f32 v100, v177, v176
	global_store_dword v[98:99], v100, off
	v_lshlrev_b32_e32 v101, 16, v11
	v_and_b32_e32 v102, 0xffff0000, v11
	v_readlane_b32 s70, v241, 10
	v_fma_f32 v177, v177, s71, v101
	v_fma_f32 v176, v176, s71, v102
	v_lshl_add_u64 v[98:99], v[98:99], 0, s[100:101]
	v_cvt_pk_bf16_f32 v100, v177, v176
	global_store_dword v[98:99], v100, off
	v_lshlrev_b32_e32 v101, 16, v12
	v_and_b32_e32 v102, 0xffff0000, v12
	v_readlane_b32 s71, v241, 11
	v_fma_f32 v177, v177, s70, v101
	v_fma_f32 v176, v176, s70, v102
	v_lshl_add_u64 v[98:99], v[98:99], 0, s[100:101]
	v_cvt_pk_bf16_f32 v100, v177, v176
	global_store_dword v[98:99], v100, off
	v_lshlrev_b32_e32 v101, 16, v13
	v_and_b32_e32 v102, 0xffff0000, v13
	v_readlane_b32 s70, v241, 12
	v_fma_f32 v177, v177, s71, v101
	v_fma_f32 v176, v176, s71, v102
	v_lshl_add_u64 v[98:99], v[98:99], 0, s[100:101]
	v_cvt_pk_bf16_f32 v100, v177, v176
	global_store_dword v[98:99], v100, off
	v_lshlrev_b32_e32 v101, 16, v14
	v_and_b32_e32 v102, 0xffff0000, v14
	v_readlane_b32 s71, v241, 13
	v_fma_f32 v177, v177, s70, v101
	v_fma_f32 v176, v176, s70, v102
	v_lshl_add_u64 v[98:99], v[98:99], 0, s[100:101]
	v_cvt_pk_bf16_f32 v100, v177, v176
	global_store_dword v[98:99], v100, off
	v_lshlrev_b32_e32 v101, 16, v15
	v_and_b32_e32 v102, 0xffff0000, v15
	v_readlane_b32 s70, v241, 14
	v_fma_f32 v177, v177, s71, v101
	v_fma_f32 v176, v176, s71, v102
	v_lshl_add_u64 v[98:99], v[98:99], 0, s[100:101]
	v_cvt_pk_bf16_f32 v100, v177, v176
	global_store_dword v[98:99], v100, off
	v_lshlrev_b32_e32 v101, 16, v16
	v_and_b32_e32 v102, 0xffff0000, v16
	v_readlane_b32 s71, v241, 15
	v_fma_f32 v177, v177, s70, v101
	v_fma_f32 v176, v176, s70, v102
	v_lshl_add_u64 v[98:99], v[98:99], 0, s[100:101]
	v_cvt_pk_bf16_f32 v100, v177, v176
	global_store_dword v[98:99], v100, off
	v_lshlrev_b32_e32 v101, 16, v17
	v_and_b32_e32 v102, 0xffff0000, v17
	v_fma_f32 v177, v177, s71, v101
	v_fma_f32 v176, v176, s71, v102
.Lsc_lo_b2:
	s_add_i32 s89, s89, 1
	s_barrier
	s_branch .Lsc_lo_loop
.Lsc_lo_done:
.LBB0_245:
	v_readlane_b32 s37, v255, 10
	s_mov_b64 s[22:23], exec
	v_readlane_b32 s16, v255, 8
	v_readlane_b32 s17, v255, 9
	s_and_b64 s[16:17], s[22:23], s[16:17]
	s_mov_b64 exec, s[16:17]
	s_cbranch_execz .LBB0_251
	s_lshl_b32 s15, s80, 8
	s_waitcnt vmcnt(0)
	v_add_u32_e32 v6, s15, v165
	s_mov_b32 s0, 0x10000
	v_cmp_gt_i32_e32 vcc, s0, v6
	s_and_b64 exec, exec, vcc
	s_cbranch_execz .LBB0_251
	s_lshl_b32 s16, s12, 8
	s_add_i32 s16, s16, s15
	v_mov_b32_e32 v0, 0xff
	v_bitop3_b16 v7, s16, v164, v0 bitop3:0xf8
	s_mov_b64 s[26:27], 0
